# MLA unit epilogue de-serialised: the eight 8-byte gate loads issued together, counted vmcnt waits, stores at the end (was load-wait-store ladder)
# speedup vs baseline: 1.0196x; 1.0196x over previous
; __device__ __forceinline__ unsigned cvt_pk_bf16(float lo, float hi) { unsigned r; asm volatile("v_cvt_pk_bf16_f32 %0, %1, %2" : "=v"(r) : "v"(lo), "v"(hi)); return r; }
; __device__ __forceinline__ float fast_rcp(float x) { return __builtin_amdgcn_rcpf(x); }
; __device__ __forceinline__ float bflo(unsigned w) { return __uint_as_float(w << 16); }
; __device__ __forceinline__ float bfhi(unsigned w) { return __uint_as_float(w & 0xffff0000u); }
; __device__ __forceinline__ void mla_unit(int h, int qb, const bf16_t* __restrict__ Qm, const bf16_t* __restrict__ Km, const bf16_t* __restrict__ Kr, const bf16_t* __restrict__ Vm, bf16_t* ZM, LAS char* lds) {
;     ...
;     l += __shfl_xor(l, 32); const float rl = fast_rcp(l);
;     bf16_t* zp = ZM + (size_t)qrow * 1024 + h * 64 + 4 * hi;
; #pragma unroll
;     for (int db = 0; db < 2; ++db)
; #pragma unroll
;         for (int g4 = 0; g4 < 4; ++g4) { bf16_t* p = zp + 32 * db + 8 * g4; const u32x2 z = *(const u32x2*)p; const f32x16& o = db ? o1 : o0;
;             u32x2 w; w.x = cvt_pk_bf16(o[4 * g4] * rl * bflo(z.x), o[4 * g4 + 1] * rl * bfhi(z.x)); w.y = cvt_pk_bf16(o[4 * g4 + 2] * rl * bflo(z.y), o[4 * g4 + 3] * rl * bfhi(z.y));
;             *(u32x2*)p = w; }
.LBB0_741:
	s_waitcnt vmcnt(0)
	v_lshlrev_b64 v[2:3], 11, v[188:189]
	v_lshl_add_u64 v[2:3], s[20:21], 0, v[2:3]
	v_lshl_add_u64 v[2:3], s[24:25], 1, v[2:3]
	v_lshlrev_b32_e32 v0, 1, v208
	v_lshl_add_u64 v[2:3], v[2:3], 0, v[0:1]
	global_load_dwordx2 v[64:65], v[2:3], off offset:0
	global_load_dwordx2 v[66:67], v[2:3], off offset:16
	global_load_dwordx2 v[68:69], v[2:3], off offset:32
	global_load_dwordx2 v[70:71], v[2:3], off offset:48
	global_load_dwordx2 v[72:73], v[2:3], off offset:64
	global_load_dwordx2 v[74:75], v[2:3], off offset:80
	global_load_dwordx2 v[76:77], v[2:3], off offset:96
	global_load_dwordx2 v[78:79], v[2:3], off offset:112
	v_mov_b32_e32 v14, v209
	s_nop 1
	v_permlane32_swap_b32_e32 v209, v14
	v_add_f32_e32 v209, v209, v14
	v_rcp_f32_e32 v0, v209
	s_waitcnt vmcnt(7)
	v_lshlrev_b32_e32 v6, 16, v64
	v_and_b32_e32 v7, 0xffff0000, v64
	v_lshlrev_b32_e32 v8, 16, v65
	v_and_b32_e32 v9, 0xffff0000, v65
	v_mul_f32_e32 v32, v32, v0
	v_mul_f32_e32 v33, v33, v0
	v_mul_f32_e32 v34, v34, v0
	v_mul_f32_e32 v35, v35, v0
	v_mul_f32_e32 v32, v32, v6
	v_mul_f32_e32 v33, v33, v7
	v_mul_f32_e32 v34, v34, v8
	v_mul_f32_e32 v35, v35, v9
	v_cvt_pk_bf16_f32 v64, v32, v33
	v_cvt_pk_bf16_f32 v65, v34, v35
	s_waitcnt vmcnt(6)
	v_lshlrev_b32_e32 v6, 16, v66
	v_and_b32_e32 v7, 0xffff0000, v66
	v_lshlrev_b32_e32 v8, 16, v67
	v_and_b32_e32 v9, 0xffff0000, v67
	v_mul_f32_e32 v36, v36, v0
	v_mul_f32_e32 v37, v37, v0
	v_mul_f32_e32 v38, v38, v0
	v_mul_f32_e32 v39, v39, v0
	v_mul_f32_e32 v36, v36, v6
	v_mul_f32_e32 v37, v37, v7
	v_mul_f32_e32 v38, v38, v8
	v_mul_f32_e32 v39, v39, v9
	v_cvt_pk_bf16_f32 v66, v36, v37
	v_cvt_pk_bf16_f32 v67, v38, v39
	s_waitcnt vmcnt(5)
	v_lshlrev_b32_e32 v6, 16, v68
	v_and_b32_e32 v7, 0xffff0000, v68
	v_lshlrev_b32_e32 v8, 16, v69
	v_and_b32_e32 v9, 0xffff0000, v69
	v_mul_f32_e32 v40, v40, v0
	v_mul_f32_e32 v41, v41, v0
	v_mul_f32_e32 v42, v42, v0
	v_mul_f32_e32 v43, v43, v0
	v_mul_f32_e32 v40, v40, v6
	v_mul_f32_e32 v41, v41, v7
	v_mul_f32_e32 v42, v42, v8
	v_mul_f32_e32 v43, v43, v9
	v_cvt_pk_bf16_f32 v68, v40, v41
	v_cvt_pk_bf16_f32 v69, v42, v43
	s_waitcnt vmcnt(4)
	v_lshlrev_b32_e32 v6, 16, v70
	v_and_b32_e32 v7, 0xffff0000, v70
	v_lshlrev_b32_e32 v8, 16, v71
	v_and_b32_e32 v9, 0xffff0000, v71
	v_mul_f32_e32 v44, v44, v0
	v_mul_f32_e32 v45, v45, v0
	v_mul_f32_e32 v46, v46, v0
	v_mul_f32_e32 v47, v47, v0
	v_mul_f32_e32 v44, v44, v6
	v_mul_f32_e32 v45, v45, v7
	v_mul_f32_e32 v46, v46, v8
	v_mul_f32_e32 v47, v47, v9
	v_cvt_pk_bf16_f32 v70, v44, v45
	v_cvt_pk_bf16_f32 v71, v46, v47
	s_waitcnt vmcnt(3)
	v_lshlrev_b32_e32 v6, 16, v72
	v_and_b32_e32 v7, 0xffff0000, v72
	v_lshlrev_b32_e32 v8, 16, v73
	v_and_b32_e32 v9, 0xffff0000, v73
	v_mul_f32_e32 v16, v16, v0
	v_mul_f32_e32 v17, v17, v0
	v_mul_f32_e32 v18, v18, v0
	v_mul_f32_e32 v19, v19, v0
	v_mul_f32_e32 v16, v16, v6
	v_mul_f32_e32 v17, v17, v7
	v_mul_f32_e32 v18, v18, v8
	v_mul_f32_e32 v19, v19, v9
	v_cvt_pk_bf16_f32 v72, v16, v17
	v_cvt_pk_bf16_f32 v73, v18, v19
	s_waitcnt vmcnt(2)
	v_lshlrev_b32_e32 v6, 16, v74
	v_and_b32_e32 v7, 0xffff0000, v74
	v_lshlrev_b32_e32 v8, 16, v75
	v_and_b32_e32 v9, 0xffff0000, v75
	v_mul_f32_e32 v20, v20, v0
	v_mul_f32_e32 v21, v21, v0
	v_mul_f32_e32 v22, v22, v0
	v_mul_f32_e32 v23, v23, v0
	v_mul_f32_e32 v20, v20, v6
	v_mul_f32_e32 v21, v21, v7
	v_mul_f32_e32 v22, v22, v8
	v_mul_f32_e32 v23, v23, v9
	v_cvt_pk_bf16_f32 v74, v20, v21
	v_cvt_pk_bf16_f32 v75, v22, v23
	s_waitcnt vmcnt(1)
	v_lshlrev_b32_e32 v6, 16, v76
	v_and_b32_e32 v7, 0xffff0000, v76
	v_lshlrev_b32_e32 v8, 16, v77
	v_and_b32_e32 v9, 0xffff0000, v77
	v_mul_f32_e32 v24, v24, v0
	v_mul_f32_e32 v25, v25, v0
	v_mul_f32_e32 v26, v26, v0
	v_mul_f32_e32 v27, v27, v0
	v_mul_f32_e32 v24, v24, v6
	v_mul_f32_e32 v25, v25, v7
	v_mul_f32_e32 v26, v26, v8
	v_mul_f32_e32 v27, v27, v9
	v_cvt_pk_bf16_f32 v76, v24, v25
	v_cvt_pk_bf16_f32 v77, v26, v27
	s_waitcnt vmcnt(0)
	v_lshlrev_b32_e32 v6, 16, v78
	v_and_b32_e32 v7, 0xffff0000, v78
	v_lshlrev_b32_e32 v8, 16, v79
	v_and_b32_e32 v9, 0xffff0000, v79
	v_mul_f32_e32 v28, v28, v0
	v_mul_f32_e32 v29, v29, v0
	v_mul_f32_e32 v30, v30, v0
	v_mul_f32_e32 v31, v31, v0
	v_mul_f32_e32 v28, v28, v6
	v_mul_f32_e32 v29, v29, v7
	v_mul_f32_e32 v30, v30, v8
	v_mul_f32_e32 v31, v31, v9
	v_cvt_pk_bf16_f32 v78, v28, v29
	v_cvt_pk_bf16_f32 v79, v30, v31
	global_store_dwordx2 v[2:3], v[64:65], off offset:0
	global_store_dwordx2 v[2:3], v[66:67], off offset:16
	global_store_dwordx2 v[2:3], v[68:69], off offset:32
	global_store_dwordx2 v[2:3], v[70:71], off offset:48
	global_store_dwordx2 v[2:3], v[72:73], off offset:64
	global_store_dwordx2 v[2:3], v[74:75], off offset:80
	global_store_dwordx2 v[2:3], v[76:77], off offset:96
	global_store_dwordx2 v[2:3], v[78:79], off offset:112
	s_add_i32 s38, s38, s3
	s_cmpk_gt_i32 s38, 0xff
	s_cbranch_scc1 .LBB0_738
